# speedup vs baseline: 1.0205x; 1.0017x over previous
; #define PG8_STAGE(bufoff, gbase, voff) do { _Pragma("unroll") for (int _i = 0; _i < 2; ++_i) \
;         __builtin_amdgcn_global_load_lds((const unsigned*)((const char*)(gbase) + (voff)[_i]), (LAS unsigned*)(lds + (bufoff) + ldsw + _i * 8192), 16, 0, 0); } while (0)
; #define PG8_LDA(dst, b, h) do { _Pragma("unroll") for (int m = 0; m < 4; ++m) _Pragma("unroll") for (int k = 0; k < 2; ++k) dst[m][k] = *(const LAS bf16x8*)(lds + PG8_SA(b, h) + aoff + m * 2048 + k * 1024); } while (0)
; #define PG8_LDB(dst, b, h) do { _Pragma("unroll") for (int n = 0; n < 2; ++n) _Pragma("unroll") for (int k = 0; k < 2; ++k) dst[n][k] = *(const LAS bf16x8*)(lds + PG8_SB(b, h) + boff + n * 2048 + k * 1024); } while (0)
; #define PG8_MMA(ai, bj, At, Bt) do { __builtin_amdgcn_s_setprio(1); _Pragma("unroll") for (int m = 0; m < 4; ++m) _Pragma("unroll") for (int n = 0; n < 2; ++n) _Pragma("unroll") for (int k = 0; k < 2; ++k) \
;         acc[ai][bj][m][n] = __builtin_amdgcn_mfma_f32_16x16x32_bf16(Bt[n][k], At[m][k], acc[ai][bj][m][n], 0, 0, 0); __builtin_amdgcn_s_setprio(0); } while (0)
; #define PG8_WAIT_L(n) asm volatile("s_waitcnt lgkmcnt(" #n ")" ::: "memory")
; #define PG8_BAR __builtin_amdgcn_s_barrier()
; #define PG8_SCHED __builtin_amdgcn_sched_barrier(0)
; template <class Epi>
; __device__ __forceinline__ void gemm_phase(const int tid, LAS unsigned char* lds, const Gemm g, const StaticOrder& S, const Epi& E) {
;     ...
;             PG8_LDB(B0, 0, 0); PG8_SCHED; PG8_LDA(At, 0, 0);
;             PG8_WAIT_L(8); PG8_BAR; PG8_WAIT_L(0); PG8_MMA(0, 0, At, B0); PG8_BAR; PG8_SCHED;
;             PG8_LDB(B1, 0, 1); PG8_STAGE(PG8_SB(0, 0), b2, voffB);
;             PG8_BAR; PG8_WAIT_L(0); PG8_MMA(0, 1, At, B1); PG8_BAR;
;             PG8_LDA(At, 0, 1); PG8_STAGE(PG8_SA(0, 0), a2, voffA);
;             PG8_BAR; PG8_WAIT_L(0); PG8_MMA(1, 0, At, B0); PG8_BAR; PG8_SCHED;
;             PG8_STAGE(PG8_SB(0, 1), b2 + hstep, voffB);
.LBB0_336:
	s_add_i32 s51, 0, 0x10000
	v_add_u32_e32 v0, s51, v221
	ds_read_b128 v[130:133], v0
	ds_read_b128 v[134:137], v0 offset:1024
	ds_read_b128 v[138:141], v0 offset:2048
	ds_read_b128 v[142:145], v0 offset:3072
	s_cmp_eq_u32 s50, 28
	s_cselect_b32 s1, s24, s39
	s_cselect_b32 s0, s25, s28
	s_cselect_b32 s11, s23, s49
	s_cselect_b32 s10, s27, s48
	ds_read_b128 v[146:149], v225
	ds_read_b128 v[150:153], v225 offset:1024
	ds_read_b128 v[154:157], v225 offset:2048
	ds_read_b128 v[158:161], v225 offset:3072
	ds_read_b128 v[162:165], v225 offset:4096
	ds_read_b128 v[166:169], v225 offset:5120
	ds_read_b128 v[170:173], v225 offset:6144
	ds_read_b128 v[174:177], v225 offset:7168
	s_waitcnt lgkmcnt(8)
	s_barrier
	s_setprio 1
	s_waitcnt lgkmcnt(7)
	v_mfma_f32_16x16x32_bf16 v[126:129], v[130:133], v[146:149], v[126:129]
	v_mfma_f32_16x16x32_bf16 v[122:125], v[138:141], v[146:149], v[122:125]
	s_waitcnt lgkmcnt(5)
	v_mfma_f32_16x16x32_bf16 v[110:113], v[130:133], v[154:157], v[110:113]
	v_mfma_f32_16x16x32_bf16 v[106:109], v[138:141], v[154:157], v[106:109]
	s_waitcnt lgkmcnt(3)
	v_mfma_f32_16x16x32_bf16 v[94:97], v[130:133], v[162:165], v[94:97]
	v_mfma_f32_16x16x32_bf16 v[90:93], v[138:141], v[162:165], v[90:93]
	s_waitcnt lgkmcnt(1)
	v_mfma_f32_16x16x32_bf16 v[78:81], v[130:133], v[170:173], v[78:81]
	v_mfma_f32_16x16x32_bf16 v[74:77], v[138:141], v[170:173], v[74:77]
	v_mfma_f32_16x16x32_bf16 v[126:129], v[134:137], v[150:153], v[126:129]
	v_mfma_f32_16x16x32_bf16 v[122:125], v[142:145], v[150:153], v[122:125]
	v_mfma_f32_16x16x32_bf16 v[110:113], v[134:137], v[158:161], v[110:113]
	v_mfma_f32_16x16x32_bf16 v[106:109], v[142:145], v[158:161], v[106:109]
	v_mfma_f32_16x16x32_bf16 v[94:97], v[134:137], v[166:169], v[94:97]
	v_mfma_f32_16x16x32_bf16 v[90:93], v[142:145], v[166:169], v[90:93]
	s_waitcnt lgkmcnt(0)
	v_mfma_f32_16x16x32_bf16 v[78:81], v[134:137], v[174:177], v[78:81]
	v_mfma_f32_16x16x32_bf16 v[74:77], v[142:145], v[174:177], v[74:77]
	s_setprio 0
	s_barrier
	s_add_i32 s54, 0, 0x14000
	s_add_i32 s51, s51, s37
	v_add_u32_e32 v0, s54, v221
	s_mov_b32 m0, s51
	ds_read_b128 v[178:181], v0
	ds_read_b128 v[182:185], v0 offset:1024
	ds_read_b128 v[186:189], v0 offset:2048
	ds_read_b128 v[190:193], v0 offset:3072
	global_load_lds_dwordx4 v198, s[10:11]
	s_add_i32 m0, s51, 0x2000
	s_nop 0
	global_load_lds_dwordx4 v194, s[10:11]
	s_barrier
	s_setprio 1
	s_waitcnt lgkmcnt(3)
	v_mfma_f32_16x16x32_bf16 v[118:121], v[178:181], v[146:149], v[118:121]
	s_waitcnt lgkmcnt(1)
	v_mfma_f32_16x16x32_bf16 v[114:117], v[186:189], v[146:149], v[114:117]
	v_mfma_f32_16x16x32_bf16 v[102:105], v[178:181], v[154:157], v[102:105]
	v_mfma_f32_16x16x32_bf16 v[98:101], v[186:189], v[154:157], v[98:101]
	v_mfma_f32_16x16x32_bf16 v[86:89], v[178:181], v[162:165], v[86:89]
	v_mfma_f32_16x16x32_bf16 v[82:85], v[186:189], v[162:165], v[82:85]
	v_mfma_f32_16x16x32_bf16 v[70:73], v[178:181], v[170:173], v[70:73]
	v_mfma_f32_16x16x32_bf16 v[66:69], v[186:189], v[170:173], v[66:69]
	v_mfma_f32_16x16x32_bf16 v[118:121], v[182:185], v[150:153], v[118:121]
	s_waitcnt lgkmcnt(0)
	v_mfma_f32_16x16x32_bf16 v[114:117], v[190:193], v[150:153], v[114:117]
	v_mfma_f32_16x16x32_bf16 v[102:105], v[182:185], v[158:161], v[102:105]
	v_mfma_f32_16x16x32_bf16 v[98:101], v[190:193], v[158:161], v[98:101]
	v_mfma_f32_16x16x32_bf16 v[86:89], v[182:185], v[166:169], v[86:89]
	v_mfma_f32_16x16x32_bf16 v[82:85], v[190:193], v[166:169], v[82:85]
	v_mfma_f32_16x16x32_bf16 v[70:73], v[182:185], v[174:177], v[70:73]
	v_mfma_f32_16x16x32_bf16 v[66:69], v[190:193], v[174:177], v[66:69]
	s_setprio 0
	s_mov_b32 m0, s46
	s_barrier
	ds_read_b128 v[146:149], v225 offset:16384
	ds_read_b128 v[150:153], v225 offset:17408
	ds_read_b128 v[154:157], v225 offset:18432
	ds_read_b128 v[158:161], v225 offset:19456
	ds_read_b128 v[162:165], v225 offset:20480
	ds_read_b128 v[166:169], v225 offset:21504
	ds_read_b128 v[170:173], v225 offset:22528
	ds_read_b128 v[174:177], v225 offset:23552
	global_load_lds_dwordx4 v200, s[0:1]
	s_mov_b32 m0, s47
	s_nop 0
	global_load_lds_dwordx4 v196, s[0:1]
	s_barrier
	s_setprio 1
	s_waitcnt lgkmcnt(7)
	v_mfma_f32_16x16x32_bf16 v[62:65], v[130:133], v[146:149], v[62:65]
	v_mfma_f32_16x16x32_bf16 v[58:61], v[138:141], v[146:149], v[58:61]
	s_waitcnt lgkmcnt(5)
	v_mfma_f32_16x16x32_bf16 v[46:49], v[130:133], v[154:157], v[46:49]
	v_mfma_f32_16x16x32_bf16 v[42:45], v[138:141], v[154:157], v[42:45]
	s_waitcnt lgkmcnt(3)
	v_mfma_f32_16x16x32_bf16 v[30:33], v[130:133], v[162:165], v[30:33]
	v_mfma_f32_16x16x32_bf16 v[26:29], v[138:141], v[162:165], v[26:29]
	s_waitcnt lgkmcnt(1)
	v_mfma_f32_16x16x32_bf16 v[14:17], v[130:133], v[170:173], v[14:17]
	v_mfma_f32_16x16x32_bf16 v[10:13], v[138:141], v[170:173], v[10:13]
	v_mfma_f32_16x16x32_bf16 v[62:65], v[134:137], v[150:153], v[62:65]
	v_mfma_f32_16x16x32_bf16 v[58:61], v[142:145], v[150:153], v[58:61]
	v_mfma_f32_16x16x32_bf16 v[46:49], v[134:137], v[158:161], v[46:49]
	v_mfma_f32_16x16x32_bf16 v[42:45], v[142:145], v[158:161], v[42:45]
	v_mfma_f32_16x16x32_bf16 v[30:33], v[134:137], v[166:169], v[30:33]
	v_mfma_f32_16x16x32_bf16 v[26:29], v[142:145], v[166:169], v[26:29]
	s_waitcnt lgkmcnt(0)
	v_mfma_f32_16x16x32_bf16 v[14:17], v[134:137], v[174:177], v[14:17]
	v_mfma_f32_16x16x32_bf16 v[10:13], v[142:145], v[174:177], v[10:13]
	s_setprio 0
	s_barrier
	s_add_u32 s66, s10, 0x80000
	s_addc_u32 s67, s11, 0
	s_add_i32 s51, s54, s37
	s_mov_b32 m0, s51
	s_nop 0
	global_load_lds_dwordx4 v198, s[66:67]
	s_add_i32 m0, s51, 0x2000
	s_nop 0
	global_load_lds_dwordx4 v194, s[66:67]
	s_waitcnt vmcnt(6)
	s_barrier
; #define PG8_STAGE(bufoff, gbase, voff) do { _Pragma("unroll") for (int _i = 0; _i < 2; ++_i) \
;         __builtin_amdgcn_global_load_lds((const unsigned*)((const char*)(gbase) + (voff)[_i]), (LAS unsigned*)(lds + (bufoff) + ldsw + _i * 8192), 16, 0, 0); } while (0)
; #define PG8_LDA(dst, b, h) do { _Pragma("unroll") for (int m = 0; m < 4; ++m) _Pragma("unroll") for (int k = 0; k < 2; ++k) dst[m][k] = *(const LAS bf16x8*)(lds + PG8_SA(b, h) + aoff + m * 2048 + k * 1024); } while (0)
; #define PG8_LDB(dst, b, h) do { _Pragma("unroll") for (int n = 0; n < 2; ++n) _Pragma("unroll") for (int k = 0; k < 2; ++k) dst[n][k] = *(const LAS bf16x8*)(lds + PG8_SB(b, h) + boff + n * 2048 + k * 1024); } while (0)
; #define PG8_MMA(ai, bj, At, Bt) do { __builtin_amdgcn_s_setprio(1); _Pragma("unroll") for (int m = 0; m < 4; ++m) _Pragma("unroll") for (int n = 0; n < 2; ++n) _Pragma("unroll") for (int k = 0; k < 2; ++k) \
;         acc[ai][bj][m][n] = __builtin_amdgcn_mfma_f32_16x16x32_bf16(Bt[n][k], At[m][k], acc[ai][bj][m][n], 0, 0, 0); __builtin_amdgcn_s_setprio(0); } while (0)
; template <class Epi>
; __device__ __forceinline__ void gemm_phase(const int tid, LAS unsigned char* lds, const Gemm g, const StaticOrder& S, const Epi& E) {
;     ...
;             PG8_STAGE(PG8_SB(0, 1), b2 + hstep, voffB);
;             { const int first_ = __builtin_amdgcn_readfirstlane((ui > 0 && t == 0) ? 1 : 0);
;               if constexpr (Epi::SMIN == 8) asm volatile("s_cmp_eq_u32 %0, 0\n\ts_cbranch_scc1 .Lws_a%=\n\ts_waitcnt vmcnt(14)\n\ts_branch .Lws_b%=\n.Lws_a%=:\n\ts_waitcnt vmcnt(6)\n.Lws_b%=:" :: "s"(first_) : "memory", "scc");
;               else if constexpr (Epi::SMIN == 24) asm volatile("s_cmp_eq_u32 %0, 0\n\ts_cbranch_scc1 .Lws_a%=\n\ts_waitcnt vmcnt(30)\n\ts_branch .Lws_b%=\n.Lws_a%=:\n\ts_waitcnt vmcnt(6)\n.Lws_b%=:" :: "s"(first_) : "memory", "scc");
;               else PG8_WAIT_V(6); }
;             PG8_BAR; PG8_MMA(1, 1, At, B1); PG8_BAR;
;             PG8_LDB(B0, 1, 0); PG8_SCHED; PG8_LDA(At, 1, 0); PG8_STAGE(PG8_SA(0, 1), a2 + hstep, voffA);
;             PG8_WAIT_L(8); PG8_BAR; PG8_WAIT_L(0); PG8_MMA(0, 0, At, B0); PG8_BAR; PG8_SCHED;
;             PG8_LDB(B1, 1, 1); PG8_STAGE(PG8_SB(1, 0), b3, voffB);
;             PG8_BAR; PG8_WAIT_L(0); PG8_MMA(0, 1, At, B1); PG8_BAR;
;             PG8_LDA(At, 1, 1); PG8_STAGE(PG8_SA(1, 0), a3, voffA);
	s_setprio 1
	v_mfma_f32_16x16x32_bf16 v[54:57], v[178:181], v[146:149], v[54:57]
	v_mfma_f32_16x16x32_bf16 v[50:53], v[186:189], v[146:149], v[50:53]
	v_mfma_f32_16x16x32_bf16 v[38:41], v[178:181], v[154:157], v[38:41]
	v_mfma_f32_16x16x32_bf16 v[34:37], v[186:189], v[154:157], v[34:37]
	v_mfma_f32_16x16x32_bf16 v[22:25], v[178:181], v[162:165], v[22:25]
	v_mfma_f32_16x16x32_bf16 v[18:21], v[186:189], v[162:165], v[18:21]
	v_mfma_f32_16x16x32_bf16 v[6:9], v[178:181], v[170:173], v[6:9]
	v_mfma_f32_16x16x32_bf16 v[2:5], v[186:189], v[170:173], v[2:5]
	v_mfma_f32_16x16x32_bf16 v[54:57], v[182:185], v[150:153], v[54:57]
	v_mfma_f32_16x16x32_bf16 v[50:53], v[190:193], v[150:153], v[50:53]
	v_mfma_f32_16x16x32_bf16 v[38:41], v[182:185], v[158:161], v[38:41]
	v_mfma_f32_16x16x32_bf16 v[34:37], v[190:193], v[158:161], v[34:37]
	v_mfma_f32_16x16x32_bf16 v[22:25], v[182:185], v[166:169], v[22:25]
	v_mfma_f32_16x16x32_bf16 v[18:21], v[190:193], v[166:169], v[18:21]
	v_mfma_f32_16x16x32_bf16 v[6:9], v[182:185], v[174:177], v[6:9]
	v_mfma_f32_16x16x32_bf16 v[2:5], v[190:193], v[174:177], v[2:5]
	s_setprio 0
	s_add_i32 s51, 0, 0x18000
	v_add_u32_e32 v0, s51, v221
	s_barrier
	ds_read_b128 v[130:133], v0
	ds_read_b128 v[134:137], v0 offset:1024
	ds_read_b128 v[138:141], v0 offset:2048
	ds_read_b128 v[142:145], v0 offset:3072
	s_add_u32 s66, s0, 0x80000
	s_addc_u32 s67, s1, 0
	s_mov_b32 m0, s58
	ds_read_b128 v[146:149], v225 offset:32768
	ds_read_b128 v[150:153], v225 offset:33792
	ds_read_b128 v[154:157], v225 offset:34816
	ds_read_b128 v[158:161], v225 offset:35840
	ds_read_b128 v[162:165], v225 offset:36864
	ds_read_b128 v[166:169], v225 offset:37888
	ds_read_b128 v[170:173], v225 offset:38912
	ds_read_b128 v[174:177], v225 offset:39936
	global_load_lds_dwordx4 v200, s[66:67]
	s_mov_b32 m0, s59
	s_nop 0
	global_load_lds_dwordx4 v196, s[66:67]
	s_waitcnt lgkmcnt(8)
	s_barrier
	s_setprio 1
	s_waitcnt lgkmcnt(7)
	v_mfma_f32_16x16x32_bf16 v[126:129], v[130:133], v[146:149], v[126:129]
	v_mfma_f32_16x16x32_bf16 v[122:125], v[138:141], v[146:149], v[122:125]
	s_waitcnt lgkmcnt(5)
	v_mfma_f32_16x16x32_bf16 v[110:113], v[130:133], v[154:157], v[110:113]
	v_mfma_f32_16x16x32_bf16 v[106:109], v[138:141], v[154:157], v[106:109]
	s_waitcnt lgkmcnt(3)
	v_mfma_f32_16x16x32_bf16 v[94:97], v[130:133], v[162:165], v[94:97]
	v_mfma_f32_16x16x32_bf16 v[90:93], v[138:141], v[162:165], v[90:93]
	s_waitcnt lgkmcnt(1)
	v_mfma_f32_16x16x32_bf16 v[78:81], v[130:133], v[170:173], v[78:81]
	v_mfma_f32_16x16x32_bf16 v[74:77], v[138:141], v[170:173], v[74:77]
	v_mfma_f32_16x16x32_bf16 v[126:129], v[134:137], v[150:153], v[126:129]
	v_mfma_f32_16x16x32_bf16 v[122:125], v[142:145], v[150:153], v[122:125]
	v_mfma_f32_16x16x32_bf16 v[110:113], v[134:137], v[158:161], v[110:113]
	v_mfma_f32_16x16x32_bf16 v[106:109], v[142:145], v[158:161], v[106:109]
	v_mfma_f32_16x16x32_bf16 v[94:97], v[134:137], v[166:169], v[94:97]
	v_mfma_f32_16x16x32_bf16 v[90:93], v[142:145], v[166:169], v[90:93]
	s_waitcnt lgkmcnt(0)
	v_mfma_f32_16x16x32_bf16 v[78:81], v[134:137], v[174:177], v[78:81]
	v_mfma_f32_16x16x32_bf16 v[74:77], v[142:145], v[174:177], v[74:77]
	s_setprio 0
	s_barrier
	s_add_i32 s54, 0, 0x1c000
	s_add_i32 s51, s51, s37
	v_add_u32_e32 v0, s54, v221
	s_add_i32 m0, s51, 0xffffff80
	ds_read_b128 v[178:181], v0
	ds_read_b128 v[182:185], v0 offset:1024
	ds_read_b128 v[186:189], v0 offset:2048
	ds_read_b128 v[190:193], v0 offset:3072
	global_load_lds_dwordx4 v198, s[10:11] offset:128
	s_add_i32 m0, s51, 0x1f80
	s_nop 0
	global_load_lds_dwordx4 v194, s[10:11] offset:128
	s_barrier
	s_setprio 1
	s_waitcnt lgkmcnt(3)
	v_mfma_f32_16x16x32_bf16 v[118:121], v[178:181], v[146:149], v[118:121]
	s_waitcnt lgkmcnt(1)
	v_mfma_f32_16x16x32_bf16 v[114:117], v[186:189], v[146:149], v[114:117]
	v_mfma_f32_16x16x32_bf16 v[102:105], v[178:181], v[154:157], v[102:105]
	v_mfma_f32_16x16x32_bf16 v[98:101], v[186:189], v[154:157], v[98:101]
	v_mfma_f32_16x16x32_bf16 v[86:89], v[178:181], v[162:165], v[86:89]
	v_mfma_f32_16x16x32_bf16 v[82:85], v[186:189], v[162:165], v[82:85]
	v_mfma_f32_16x16x32_bf16 v[70:73], v[178:181], v[170:173], v[70:73]
	v_mfma_f32_16x16x32_bf16 v[66:69], v[186:189], v[170:173], v[66:69]
	v_mfma_f32_16x16x32_bf16 v[118:121], v[182:185], v[150:153], v[118:121]
	s_waitcnt lgkmcnt(0)
	v_mfma_f32_16x16x32_bf16 v[114:117], v[190:193], v[150:153], v[114:117]
	v_mfma_f32_16x16x32_bf16 v[102:105], v[182:185], v[158:161], v[102:105]
	v_mfma_f32_16x16x32_bf16 v[98:101], v[190:193], v[158:161], v[98:101]
	v_mfma_f32_16x16x32_bf16 v[86:89], v[182:185], v[166:169], v[86:89]
	v_mfma_f32_16x16x32_bf16 v[82:85], v[190:193], v[166:169], v[82:85]
	v_mfma_f32_16x16x32_bf16 v[70:73], v[182:185], v[174:177], v[70:73]
	v_mfma_f32_16x16x32_bf16 v[66:69], v[190:193], v[174:177], v[66:69]
	s_setprio 0
	s_add_i32 m0, s68, 0xffffff80
	s_barrier
	ds_read_b128 v[146:149], v225 offset:49152
	ds_read_b128 v[150:153], v225 offset:50176
	ds_read_b128 v[154:157], v225 offset:51200
	ds_read_b128 v[158:161], v225 offset:52224
	ds_read_b128 v[162:165], v225 offset:53248
	ds_read_b128 v[166:169], v225 offset:54272
	ds_read_b128 v[170:173], v225 offset:55296
	ds_read_b128 v[174:177], v225 offset:56320
	global_load_lds_dwordx4 v200, s[0:1] offset:128
	s_add_i32 m0, s69, 0xffffff80
	s_nop 0
	global_load_lds_dwordx4 v196, s[0:1] offset:128
	s_barrier
; #define PG8_STAGE(bufoff, gbase, voff) do { _Pragma("unroll") for (int _i = 0; _i < 2; ++_i) \
;         __builtin_amdgcn_global_load_lds((const unsigned*)((const char*)(gbase) + (voff)[_i]), (LAS unsigned*)(lds + (bufoff) + ldsw + _i * 8192), 16, 0, 0); } while (0)
; #define PG8_LDA(dst, b, h) do { _Pragma("unroll") for (int m = 0; m < 4; ++m) _Pragma("unroll") for (int k = 0; k < 2; ++k) dst[m][k] = *(const LAS bf16x8*)(lds + PG8_SA(b, h) + aoff + m * 2048 + k * 1024); } while (0)
; #define PG8_MMA(ai, bj, At, Bt) do { __builtin_amdgcn_s_setprio(1); _Pragma("unroll") for (int m = 0; m < 4; ++m) _Pragma("unroll") for (int n = 0; n < 2; ++n) _Pragma("unroll") for (int k = 0; k < 2; ++k) \
;         acc[ai][bj][m][n] = __builtin_amdgcn_mfma_f32_16x16x32_bf16(Bt[n][k], At[m][k], acc[ai][bj][m][n], 0, 0, 0); __builtin_amdgcn_s_setprio(0); } while (0)
; #define PG8_WAIT_V(n) asm volatile("s_waitcnt vmcnt(" #n ")" ::: "memory")
; #define PG8_WAIT_L(n) asm volatile("s_waitcnt lgkmcnt(" #n ")" ::: "memory")
; #define PG8_BAR __builtin_amdgcn_s_barrier()
; #define PG8_SCHED __builtin_amdgcn_sched_barrier(0)
; template <class Epi>
; __device__ __forceinline__ void gemm_phase(const int tid, LAS unsigned char* lds, const Gemm g, const StaticOrder& S, const Epi& E) {
;     ...
;             PG8_LDA(At, 1, 1); PG8_STAGE(PG8_SA(1, 0), a3, voffA);
;             PG8_BAR; PG8_WAIT_L(0); PG8_MMA(1, 0, At, B0); PG8_BAR; PG8_SCHED;
;             PG8_STAGE(PG8_SB(1, 1), b3 + hstep, voffB);
;             PG8_WAIT_V(6); PG8_BAR; PG8_STAGE(PG8_SA(1, 1), a3 + hstep, voffA);
;             PG8_MMA(1, 1, At, B1); PG8_BAR;
;         }
	s_setprio 1
	s_waitcnt lgkmcnt(7)
	v_mfma_f32_16x16x32_bf16 v[62:65], v[130:133], v[146:149], v[62:65]
	v_mfma_f32_16x16x32_bf16 v[58:61], v[138:141], v[146:149], v[58:61]
	s_waitcnt lgkmcnt(5)
	v_mfma_f32_16x16x32_bf16 v[46:49], v[130:133], v[154:157], v[46:49]
	v_mfma_f32_16x16x32_bf16 v[42:45], v[138:141], v[154:157], v[42:45]
	s_waitcnt lgkmcnt(3)
	v_mfma_f32_16x16x32_bf16 v[30:33], v[130:133], v[162:165], v[30:33]
	v_mfma_f32_16x16x32_bf16 v[26:29], v[138:141], v[162:165], v[26:29]
	s_waitcnt lgkmcnt(1)
	v_mfma_f32_16x16x32_bf16 v[14:17], v[130:133], v[170:173], v[14:17]
	v_mfma_f32_16x16x32_bf16 v[10:13], v[138:141], v[170:173], v[10:13]
	v_mfma_f32_16x16x32_bf16 v[62:65], v[134:137], v[150:153], v[62:65]
	v_mfma_f32_16x16x32_bf16 v[58:61], v[142:145], v[150:153], v[58:61]
	v_mfma_f32_16x16x32_bf16 v[46:49], v[134:137], v[158:161], v[46:49]
	v_mfma_f32_16x16x32_bf16 v[42:45], v[142:145], v[158:161], v[42:45]
	v_mfma_f32_16x16x32_bf16 v[30:33], v[134:137], v[166:169], v[30:33]
	v_mfma_f32_16x16x32_bf16 v[26:29], v[142:145], v[166:169], v[26:29]
	s_waitcnt lgkmcnt(0)
	v_mfma_f32_16x16x32_bf16 v[14:17], v[134:137], v[174:177], v[14:17]
	v_mfma_f32_16x16x32_bf16 v[10:13], v[142:145], v[174:177], v[10:13]
	s_setprio 0
	s_barrier
	s_add_u32 s10, s10, 0x80080
	s_addc_u32 s11, s11, 0
	s_add_i32 s51, s54, s37
	s_mov_b32 m0, s51
	s_nop 0
	global_load_lds_dwordx4 v198, s[10:11]
	s_add_i32 m0, s51, 0x2000
	s_add_u32 s0, s0, 0x80080
	s_addc_u32 s1, s1, 0
	global_load_lds_dwordx4 v194, s[10:11]
	s_mov_b32 m0, s84
	s_waitcnt vmcnt(6)
	s_barrier
	global_load_lds_dwordx4 v200, s[0:1]
	s_mov_b32 m0, s85
	s_nop 0
	global_load_lds_dwordx4 v196, s[0:1]
	s_setprio 1
	v_mfma_f32_16x16x32_bf16 v[54:57], v[178:181], v[146:149], v[54:57]
	v_mfma_f32_16x16x32_bf16 v[50:53], v[186:189], v[146:149], v[50:53]
	v_mfma_f32_16x16x32_bf16 v[38:41], v[178:181], v[154:157], v[38:41]
	v_mfma_f32_16x16x32_bf16 v[34:37], v[186:189], v[154:157], v[34:37]
	v_mfma_f32_16x16x32_bf16 v[22:25], v[178:181], v[162:165], v[22:25]
	v_mfma_f32_16x16x32_bf16 v[18:21], v[186:189], v[162:165], v[18:21]
	v_mfma_f32_16x16x32_bf16 v[6:9], v[178:181], v[170:173], v[6:9]
	v_mfma_f32_16x16x32_bf16 v[2:5], v[186:189], v[170:173], v[2:5]
	v_mfma_f32_16x16x32_bf16 v[54:57], v[182:185], v[150:153], v[54:57]
	v_mfma_f32_16x16x32_bf16 v[50:53], v[190:193], v[150:153], v[50:53]
	v_mfma_f32_16x16x32_bf16 v[38:41], v[182:185], v[158:161], v[38:41]
	v_mfma_f32_16x16x32_bf16 v[34:37], v[190:193], v[158:161], v[34:37]
	v_mfma_f32_16x16x32_bf16 v[22:25], v[182:185], v[166:169], v[22:25]
	v_mfma_f32_16x16x32_bf16 v[18:21], v[190:193], v[166:169], v[18:21]
	v_mfma_f32_16x16x32_bf16 v[6:9], v[182:185], v[174:177], v[6:9]
	v_mfma_f32_16x16x32_bf16 v[2:5], v[190:193], v[174:177], v[2:5]
	s_setprio 0
	s_add_i32 s50, s50, 2
	s_add_u32 s28, s28, 0x100
	s_addc_u32 s39, s39, 0
	s_add_u32 s48, s48, 0x100
	s_addc_u32 s49, s49, 0
	s_cmp_gt_u32 s50, 29
	s_barrier
	s_cbranch_scc0 .LBB0_336
	v_lshl_add_u32 v212, s95, 8, v220
	s_cmp_eq_u32 s26, s95
	v_or_b32_e32 v218, 16, v212
	v_or_b32_e32 v216, 32, v212
	v_or_b32_e32 v214, 48, v212
	s_cbranch_scc1 .LBB0_341
; __device__ __forceinline__ void rows_rstd4(const float* ssqp, int rbase, int fq, float (&rs)[4]) {
;     f32x4 pa_[4], pb_[4];
; #pragma unroll
;     for (int m = 0; m < 4; ++m) { const float* q = ssqp + (size_t)(rbase + m * 16) * 32 + 8 * fq; pa_[m] = *(const f32x4*)q; pb_[m] = *(const f32x4*)(q + 4); }
;     asm volatile("" ::: "memory");
; #pragma unroll
;     for (int m = 0; m < 4; ++m) { const f32x4 a = pa_[m], b = pb_[m];
;         float t = ((a[0] + a[1]) + (a[2] + a[3])) + ((b[0] + b[1]) + (b[2] + b[3]));
;         t = xadd<16>(t); t = xadd<32>(t);
;         rs[m] = __builtin_amdgcn_rsqf(t * (1.0f / DM) + EPS); }
; }
;     __device__ __forceinline__ void operator()(const AccT& acc, const pg8::Unit& u, int wr, int wc, int fr, int fq, pg8::RsCache& rsc) const {
;     ...
;         if (rsc.pm != u.pm) {
;             float r0[4], r1[4]; rows_rstd4(ssq, row0, fq, r0); rows_rstd4(ssq, row0 + 128, fq, r1);
;             if (fq == 0) {
; #pragma unroll
;                 for (int m = 0; m < 4; ++m) { rsc.rl[m * 16 + fr] = r0[m]; rsc.rl[64 + m * 16 + fr] = r1[m]; } }
;             rsc.pm = u.pm; asm volatile("s_waitcnt lgkmcnt(0)" ::: "memory"); }
	v_ashrrev_i32_e32 v213, 31, v212
	v_lshlrev_b64 v[130:131], 7, v[212:213]
	v_lshl_add_u64 v[130:131], v[204:205], 0, v[130:131]
	global_load_dwordx4 v[132:135], v[130:131], off offset:16
	global_load_dwordx4 v[136:139], v[130:131], off
	v_ashrrev_i32_e32 v219, 31, v218
	v_lshlrev_b64 v[140:141], 7, v[218:219]
	v_lshl_add_u64 v[144:145], v[204:205], 0, v[140:141]
	global_load_dwordx4 v[140:143], v[144:145], off offset:16
	s_nop 0
	global_load_dwordx4 v[144:147], v[144:145], off
	v_ashrrev_i32_e32 v217, 31, v216
	v_lshlrev_b64 v[148:149], 7, v[216:217]
	v_lshl_add_u64 v[152:153], v[204:205], 0, v[148:149]
	global_load_dwordx4 v[148:151], v[152:153], off offset:16
	s_nop 0
	global_load_dwordx4 v[152:155], v[152:153], off
	v_ashrrev_i32_e32 v215, 31, v214
	v_lshlrev_b64 v[156:157], 7, v[214:215]
	v_lshl_add_u64 v[160:161], v[204:205], 0, v[156:157]
	global_load_dwordx4 v[156:159], v[160:161], off offset:16
	s_nop 0
	global_load_dwordx4 v[160:163], v[160:161], off
	s_mov_b64 s[0:1], 0x4000
	s_waitcnt vmcnt(0)
	v_add_f32_e32 v132, v132, v133
	v_add_f32_e32 v0, v136, v137
	v_add_f32_e32 v136, v138, v139
	v_add_f32_e32 v133, v134, v135
	v_add_f32_e32 v0, v0, v136
	v_add_f32_e32 v132, v132, v133
	v_add_f32_e32 v0, v0, v132
	ds_swizzle_b32 v132, v0 offset:swizzle(SWAP,16)
	v_add_f32_e32 v133, v146, v147
	v_add_f32_e32 v134, v142, v143
	s_waitcnt lgkmcnt(0)
	v_add_f32_e32 v0, v0, v132
	v_add_f32_e32 v132, v144, v145
	v_add_f32_e32 v132, v132, v133
	v_add_f32_e32 v133, v140, v141
	v_add_f32_e32 v133, v133, v134
	v_add_f32_e32 v132, v132, v133
	ds_swizzle_b32 v133, v132 offset:swizzle(SWAP,16)
	v_add_f32_e32 v134, v150, v151
	v_mov_b32_e32 v138, v0
	s_nop 1
	v_permlane32_swap_b32_e32 v0, v138
	s_waitcnt lgkmcnt(0)
	v_add_f32_e32 v139, v132, v133
	v_add_f32_e32 v132, v152, v153
	v_add_f32_e32 v133, v154, v155
	v_add_f32_e32 v132, v132, v133
	v_add_f32_e32 v133, v148, v149
	v_add_f32_e32 v133, v133, v134
	v_add_f32_e32 v132, v132, v133
	ds_swizzle_b32 v133, v132 offset:swizzle(SWAP,16)
	v_add_f32_e32 v134, v158, v159
	v_mov_b32_e32 v140, v139
	s_nop 1
	v_permlane32_swap_b32_e32 v139, v140
	s_waitcnt lgkmcnt(0)
	v_add_f32_e32 v141, v132, v133
	v_add_f32_e32 v132, v160, v161
	v_add_f32_e32 v133, v162, v163
	v_add_f32_e32 v132, v132, v133
	v_add_f32_e32 v133, v156, v157
	v_add_f32_e32 v133, v133, v134
	v_add_f32_e32 v132, v132, v133
	ds_swizzle_b32 v133, v132 offset:swizzle(SWAP,16)
	v_mov_b32_e32 v142, v141
	s_nop 1
	v_permlane32_swap_b32_e32 v141, v142
	s_waitcnt lgkmcnt(0)
	v_add_f32_e32 v143, v132, v133
	v_lshl_add_u64 v[132:133], v[130:131], 0, s[0:1]
	s_movk_i32 s0, 0x4000
	v_add_co_u32_e32 v134, vcc, s0, v130
	s_movk_i32 s0, 0x5000
	s_nop 0
	v_addc_co_u32_e32 v135, vcc, 0, v131, vcc
	v_add_co_u32_e32 v136, vcc, s0, v130
	s_mov_b64 s[0:1], 0x4800
	s_nop 0
	v_addc_co_u32_e32 v137, vcc, 0, v131, vcc
	global_load_dwordx4 v[146:149], v[136:137], off offset:-4096
	global_load_dwordx4 v[150:153], v[132:133], off offset:16
	v_lshl_add_u64 v[132:133], v[130:131], 0, s[0:1]
	s_mov_b64 s[0:1], 0x5000
	global_load_dwordx4 v[154:157], v[134:135], off offset:2048
	global_load_dwordx4 v[158:161], v[132:133], off offset:16
	v_lshl_add_u64 v[132:133], v[130:131], 0, s[0:1]
	s_mov_b64 s[0:1], 0x5800
	v_lshl_add_u64 v[130:131], v[130:131], 0, s[0:1]
	global_load_dwordx4 v[162:165], v[136:137], off
	global_load_dwordx4 v[166:169], v[132:133], off offset:16
	s_nop 0
	global_load_dwordx4 v[134:137], v[136:137], off offset:2048
	s_nop 0
	global_load_dwordx4 v[130:133], v[130:131], off offset:16
	v_mov_b32_e32 v144, v143
	s_nop 1
	v_permlane32_swap_b32_e32 v143, v144
	s_waitcnt vmcnt(7)
	v_add_f32_e32 v145, v146, v147
	v_add_f32_e32 v146, v148, v149
	v_add_f32_e32 v145, v145, v146
	s_waitcnt vmcnt(6)
	v_add_f32_e32 v146, v150, v151
	v_add_f32_e32 v147, v152, v153
	v_add_f32_e32 v146, v146, v147
	s_waitcnt vmcnt(5)
	v_add_f32_e32 v147, v154, v155
	v_add_f32_e32 v148, v156, v157
	v_add_f32_e32 v147, v147, v148
	s_waitcnt vmcnt(4)
	v_add_f32_e32 v148, v158, v159
	v_add_f32_e32 v149, v160, v161
	v_add_f32_e32 v148, v148, v149
	s_waitcnt vmcnt(3)
	v_add_f32_e32 v149, v162, v163
	v_add_f32_e32 v150, v164, v165
	v_add_f32_e32 v149, v149, v150
	s_waitcnt vmcnt(2)
	v_add_f32_e32 v150, v166, v167
	v_add_f32_e32 v151, v168, v169
	s_waitcnt vmcnt(1)
	v_add_f32_e32 v134, v134, v135
	v_add_f32_e32 v135, v136, v137
	s_waitcnt vmcnt(0)
	v_add_f32_e32 v130, v130, v131
	v_add_f32_e32 v131, v132, v133
	v_add_f32_e32 v150, v150, v151
	v_add_f32_e32 v134, v134, v135
	v_add_f32_e32 v130, v130, v131
	v_add_f32_e32 v145, v145, v146
	v_add_f32_e32 v147, v147, v148
	v_add_f32_e32 v149, v149, v150
	v_add_f32_e32 v130, v134, v130
	ds_swizzle_b32 v146, v145 offset:swizzle(SWAP,16)
	ds_swizzle_b32 v148, v147 offset:swizzle(SWAP,16)
	ds_swizzle_b32 v150, v149 offset:swizzle(SWAP,16)
	ds_swizzle_b32 v131, v130 offset:swizzle(SWAP,16)
	s_waitcnt lgkmcnt(3)
	v_add_f32_e32 v145, v145, v146
	s_waitcnt lgkmcnt(2)
	v_add_f32_e32 v147, v147, v148
	s_waitcnt lgkmcnt(1)
	v_add_f32_e32 v149, v149, v150
	s_waitcnt lgkmcnt(0)
	v_add_f32_e32 v130, v130, v131
	v_mov_b32_e32 v146, v145
	v_mov_b32_e32 v148, v147
	v_mov_b32_e32 v150, v149
	v_mov_b32_e32 v131, v130
	v_permlane32_swap_b32_e32 v145, v146
	v_permlane32_swap_b32_e32 v147, v148
	v_permlane32_swap_b32_e32 v149, v150
	v_permlane32_swap_b32_e32 v130, v131
	s_and_saveexec_b64 s[0:1], s[4:5]
	s_cbranch_execz .LBB0_340
	v_add_f32_e32 v136, v139, v140
	v_add_f32_e32 v0, v0, v138
	v_add_f32_e32 v132, v147, v148
	v_add_f32_e32 v133, v145, v146
	v_fmamk_f32 v136, v136, 0x3a000000, v242
	v_fmamk_f32 v0, v0, 0x3a000000, v242
	v_fmamk_f32 v132, v132, 0x3a000000, v242
	v_fmamk_f32 v133, v133, 0x3a000000, v242
	v_add_f32_e32 v134, v143, v144
	v_add_f32_e32 v135, v141, v142
	v_rsq_f32_e32 v136, v136
	v_rsq_f32_e32 v0, v0
	v_add_f32_e32 v130, v130, v131
	v_add_f32_e32 v131, v149, v150
	v_rsq_f32_e32 v132, v132
	v_rsq_f32_e32 v133, v133
	v_fmamk_f32 v134, v134, 0x3a000000, v242
	v_fmamk_f32 v135, v135, 0x3a000000, v242
	v_fmamk_f32 v130, v130, 0x3a000000, v242
	v_fmamk_f32 v131, v131, 0x3a000000, v242
	v_rsq_f32_e32 v134, v134
	v_rsq_f32_e32 v135, v135
	v_rsq_f32_e32 v130, v130
	v_rsq_f32_e32 v131, v131
	ds_write2_b32 v222, v0, v136 offset1:16
	ds_write2_b32 v222, v133, v132 offset0:64 offset1:80
	ds_write2_b32 v222, v135, v134 offset0:32 offset1:48
	ds_write2_b32 v222, v131, v130 offset0:96 offset1:112

; #define PG8_STAGE(bufoff, gbase, voff) do { _Pragma("unroll") for (int _i = 0; _i < 2; ++_i) \
;         __builtin_amdgcn_global_load_lds((const unsigned*)((const char*)(gbase) + (voff)[_i]), (LAS unsigned*)(lds + (bufoff) + ldsw + _i * 8192), 16, 0, 0); } while (0)
; #define PG8_LDA(dst, b, h) do { _Pragma("unroll") for (int m = 0; m < 4; ++m) _Pragma("unroll") for (int k = 0; k < 2; ++k) dst[m][k] = *(const LAS bf16x8*)(lds + PG8_SA(b, h) + aoff + m * 2048 + k * 1024); } while (0)
; #define PG8_LDB(dst, b, h) do { _Pragma("unroll") for (int n = 0; n < 2; ++n) _Pragma("unroll") for (int k = 0; k < 2; ++k) dst[n][k] = *(const LAS bf16x8*)(lds + PG8_SB(b, h) + boff + n * 2048 + k * 1024); } while (0)
; #define PG8_MMA(ai, bj, At, Bt) do { __builtin_amdgcn_s_setprio(1); _Pragma("unroll") for (int m = 0; m < 4; ++m) _Pragma("unroll") for (int n = 0; n < 2; ++n) _Pragma("unroll") for (int k = 0; k < 2; ++k) \
;         acc[ai][bj][m][n] = __builtin_amdgcn_mfma_f32_16x16x32_bf16(Bt[n][k], At[m][k], acc[ai][bj][m][n], 0, 0, 0); __builtin_amdgcn_s_setprio(0); } while (0)
; #define PG8_BAR __builtin_amdgcn_s_barrier()
; template <class Epi>
; __device__ __forceinline__ void gemm_phase(const int tid, LAS unsigned char* lds, const Gemm g, const StaticOrder& S, const Epi& E) {
;     ...
;             PG8_LDB(B0, 0, 0); PG8_SCHED; PG8_LDA(At, 0, 0);
;             PG8_WAIT_L(8); PG8_BAR; PG8_WAIT_L(0); PG8_MMA(0, 0, At, B0); PG8_BAR; PG8_SCHED;
;             PG8_LDB(B1, 0, 1); PG8_STAGE(PG8_SB(0, 0), b2, voffB);
;             PG8_BAR; PG8_WAIT_L(0); PG8_MMA(0, 1, At, B1); PG8_BAR;
;             PG8_LDA(At, 0, 1); PG8_STAGE(PG8_SA(0, 0), a2, voffA);
;             PG8_BAR; PG8_WAIT_L(0); PG8_MMA(1, 0, At, B0); PG8_BAR; PG8_SCHED;
;             PG8_STAGE(PG8_SB(0, 1), b2 + hstep, voffB);
;             { const int first_ = __builtin_amdgcn_readfirstlane((ui > 0 && t == 0) ? 1 : 0);
;               if constexpr (Epi::SMIN == 8) asm volatile("s_cmp_eq_u32 %0, 0\n\ts_cbranch_scc1 .Lws_a%=\n\ts_waitcnt vmcnt(14)\n\ts_branch .Lws_b%=\n.Lws_a%=:\n\ts_waitcnt vmcnt(6)\n.Lws_b%=:" :: "s"(first_) : "memory", "scc");
;               else if constexpr (Epi::SMIN == 24) asm volatile("s_cmp_eq_u32 %0, 0\n\ts_cbranch_scc1 .Lws_a%=\n\ts_waitcnt vmcnt(30)\n\ts_branch .Lws_b%=\n.Lws_a%=:\n\ts_waitcnt vmcnt(6)\n.Lws_b%=:" :: "s"(first_) : "memory", "scc");
;               else PG8_WAIT_V(6); }
.LBB0_448:
	s_add_i32 s66, 0, 0x10000
	v_add_u32_e32 v150, s66, v155
	ds_read_b128 v[130:133], v150
	ds_read_b128 v[142:145], v150 offset:1024
	ds_read_b128 v[146:149], v150 offset:2048
	ds_read_b128 v[150:153], v150 offset:3072
	s_cmp_eq_u32 s65, 28
	s_cselect_b32 s25, s13, s60
	s_cselect_b32 s24, s57, s59
	s_cselect_b32 s37, s11, s64
	s_cselect_b32 s36, s58, s61
	ds_read_b128 v[160:163], v158
	ds_read_b128 v[164:167], v158 offset:1024
	ds_read_b128 v[168:171], v158 offset:2048
	ds_read_b128 v[172:175], v158 offset:3072
	ds_read_b128 v[176:179], v158 offset:4096
	ds_read_b128 v[180:183], v158 offset:5120
	ds_read_b128 v[184:187], v158 offset:6144
	ds_read_b128 v[188:191], v158 offset:7168
	s_waitcnt lgkmcnt(8)
	s_barrier
	s_setprio 1
	s_waitcnt lgkmcnt(7)
	v_mfma_f32_16x16x32_bf16 v[126:129], v[130:133], v[160:163], v[126:129]
	v_mfma_f32_16x16x32_bf16 v[118:121], v[146:149], v[160:163], v[118:121]
	s_waitcnt lgkmcnt(5)
	v_mfma_f32_16x16x32_bf16 v[110:113], v[130:133], v[168:171], v[110:113]
	v_mfma_f32_16x16x32_bf16 v[102:105], v[146:149], v[168:171], v[102:105]
	s_waitcnt lgkmcnt(3)
	v_mfma_f32_16x16x32_bf16 v[94:97], v[130:133], v[176:179], v[94:97]
	v_mfma_f32_16x16x32_bf16 v[86:89], v[146:149], v[176:179], v[86:89]
	s_waitcnt lgkmcnt(1)
	v_mfma_f32_16x16x32_bf16 v[78:81], v[130:133], v[184:187], v[78:81]
	v_mfma_f32_16x16x32_bf16 v[70:73], v[146:149], v[184:187], v[70:73]
	v_mfma_f32_16x16x32_bf16 v[126:129], v[142:145], v[164:167], v[126:129]
	v_mfma_f32_16x16x32_bf16 v[118:121], v[150:153], v[164:167], v[118:121]
	v_mfma_f32_16x16x32_bf16 v[110:113], v[142:145], v[172:175], v[110:113]
	v_mfma_f32_16x16x32_bf16 v[102:105], v[150:153], v[172:175], v[102:105]
	v_mfma_f32_16x16x32_bf16 v[94:97], v[142:145], v[180:183], v[94:97]
	v_mfma_f32_16x16x32_bf16 v[86:89], v[150:153], v[180:183], v[86:89]
	s_waitcnt lgkmcnt(0)
	v_mfma_f32_16x16x32_bf16 v[78:81], v[142:145], v[188:191], v[78:81]
	v_mfma_f32_16x16x32_bf16 v[70:73], v[150:153], v[188:191], v[70:73]
	s_setprio 0
	s_barrier
	s_add_i32 s68, 0, 0x14000
	s_add_i32 s66, s66, s28
	v_add_u32_e32 v159, s68, v155
	s_mov_b32 m0, s66
	ds_read_b128 v[192:195], v159
	ds_read_b128 v[196:199], v159 offset:1024
	ds_read_b128 v[200:203], v159 offset:2048
	ds_read_b128 v[204:207], v159 offset:3072
	global_load_lds_dwordx4 v0, s[36:37]
	s_add_i32 m0, s66, 0x2000
	s_nop 0
	global_load_lds_dwordx4 v134, s[36:37]
	s_barrier
	s_setprio 1
	s_waitcnt lgkmcnt(3)
	v_mfma_f32_16x16x32_bf16 v[122:125], v[192:195], v[160:163], v[122:125]
	s_waitcnt lgkmcnt(1)
	v_mfma_f32_16x16x32_bf16 v[114:117], v[200:203], v[160:163], v[114:117]
	v_mfma_f32_16x16x32_bf16 v[106:109], v[192:195], v[168:171], v[106:109]
	v_mfma_f32_16x16x32_bf16 v[98:101], v[200:203], v[168:171], v[98:101]
	v_mfma_f32_16x16x32_bf16 v[90:93], v[192:195], v[176:179], v[90:93]
	v_mfma_f32_16x16x32_bf16 v[82:85], v[200:203], v[176:179], v[82:85]
	v_mfma_f32_16x16x32_bf16 v[74:77], v[192:195], v[184:187], v[74:77]
	v_mfma_f32_16x16x32_bf16 v[66:69], v[200:203], v[184:187], v[66:69]
	v_mfma_f32_16x16x32_bf16 v[122:125], v[196:199], v[164:167], v[122:125]
	s_waitcnt lgkmcnt(0)
	v_mfma_f32_16x16x32_bf16 v[114:117], v[204:207], v[164:167], v[114:117]
	v_mfma_f32_16x16x32_bf16 v[106:109], v[196:199], v[172:175], v[106:109]
	v_mfma_f32_16x16x32_bf16 v[98:101], v[204:207], v[172:175], v[98:101]
	v_mfma_f32_16x16x32_bf16 v[90:93], v[196:199], v[180:183], v[90:93]
	v_mfma_f32_16x16x32_bf16 v[82:85], v[204:207], v[180:183], v[82:85]
	v_mfma_f32_16x16x32_bf16 v[74:77], v[196:199], v[188:191], v[74:77]
	v_mfma_f32_16x16x32_bf16 v[66:69], v[204:207], v[188:191], v[66:69]
	s_setprio 0
	s_mov_b32 m0, s30
	s_barrier
	ds_read_b128 v[160:163], v158 offset:16384
	ds_read_b128 v[164:167], v158 offset:17408
	ds_read_b128 v[168:171], v158 offset:18432
	ds_read_b128 v[172:175], v158 offset:19456
	ds_read_b128 v[176:179], v158 offset:20480
	ds_read_b128 v[180:183], v158 offset:21504
	ds_read_b128 v[184:187], v158 offset:22528
	ds_read_b128 v[188:191], v158 offset:23552
	global_load_lds_dwordx4 v138, s[24:25]
	s_mov_b32 m0, s38
	s_nop 0
	global_load_lds_dwordx4 v136, s[24:25]
	s_barrier
	s_setprio 1
	s_waitcnt lgkmcnt(7)
	v_mfma_f32_16x16x32_bf16 v[62:65], v[130:133], v[160:163], v[62:65]
	v_mfma_f32_16x16x32_bf16 v[54:57], v[146:149], v[160:163], v[54:57]
	s_waitcnt lgkmcnt(5)
	v_mfma_f32_16x16x32_bf16 v[46:49], v[130:133], v[168:171], v[46:49]
	v_mfma_f32_16x16x32_bf16 v[38:41], v[146:149], v[168:171], v[38:41]
	s_waitcnt lgkmcnt(3)
	v_mfma_f32_16x16x32_bf16 v[30:33], v[130:133], v[176:179], v[30:33]
	v_mfma_f32_16x16x32_bf16 v[22:25], v[146:149], v[176:179], v[22:25]
	s_waitcnt lgkmcnt(1)
	v_mfma_f32_16x16x32_bf16 v[14:17], v[130:133], v[184:187], v[14:17]
	v_mfma_f32_16x16x32_bf16 v[6:9], v[146:149], v[184:187], v[6:9]
	v_mfma_f32_16x16x32_bf16 v[62:65], v[142:145], v[164:167], v[62:65]
	v_mfma_f32_16x16x32_bf16 v[54:57], v[150:153], v[164:167], v[54:57]
	v_mfma_f32_16x16x32_bf16 v[46:49], v[142:145], v[172:175], v[46:49]
	v_mfma_f32_16x16x32_bf16 v[38:41], v[150:153], v[172:175], v[38:41]
	v_mfma_f32_16x16x32_bf16 v[30:33], v[142:145], v[180:183], v[30:33]
	v_mfma_f32_16x16x32_bf16 v[22:25], v[150:153], v[180:183], v[22:25]
	s_waitcnt lgkmcnt(0)
	v_mfma_f32_16x16x32_bf16 v[14:17], v[142:145], v[188:191], v[14:17]
	v_mfma_f32_16x16x32_bf16 v[6:9], v[150:153], v[188:191], v[6:9]
	s_setprio 0
	s_barrier
	s_add_u32 s66, s36, 0x80000
	s_addc_u32 s67, s37, 0
	s_add_i32 s68, s68, s28
	s_mov_b32 m0, s68
	s_nop 0
	global_load_lds_dwordx4 v0, s[66:67]
	s_add_i32 m0, s68, 0x2000
	s_cmp_eq_u32 s65, -2
	global_load_lds_dwordx4 v134, s[66:67]
	s_cselect_b64 s[66:67], -1, 0
	s_and_b64 s[66:67], s[22:23], s[66:67]
	v_cndmask_b32_e64 v130, 0, 1, s[66:67]
	s_nop 0
	v_readfirstlane_b32 s66, v130
	s_and_b32 s66, s66, 1
	s_cmp_eq_u32 s66, 0
	s_cbranch_scc1 .Lws_a1
	s_waitcnt vmcnt(14)
	s_branch .Lws_b1

; #define PG8_STAGE(bufoff, gbase, voff) do { _Pragma("unroll") for (int _i = 0; _i < 2; ++_i) \
;         __builtin_amdgcn_global_load_lds((const unsigned*)((const char*)(gbase) + (voff)[_i]), (LAS unsigned*)(lds + (bufoff) + ldsw + _i * 8192), 16, 0, 0); } while (0)
; #define PG8_LDA(dst, b, h) do { _Pragma("unroll") for (int m = 0; m < 4; ++m) _Pragma("unroll") for (int k = 0; k < 2; ++k) dst[m][k] = *(const LAS bf16x8*)(lds + PG8_SA(b, h) + aoff + m * 2048 + k * 1024); } while (0)
; #define PG8_LDB(dst, b, h) do { _Pragma("unroll") for (int n = 0; n < 2; ++n) _Pragma("unroll") for (int k = 0; k < 2; ++k) dst[n][k] = *(const LAS bf16x8*)(lds + PG8_SB(b, h) + boff + n * 2048 + k * 1024); } while (0)
; #define PG8_MMA(ai, bj, At, Bt) do { __builtin_amdgcn_s_setprio(1); _Pragma("unroll") for (int m = 0; m < 4; ++m) _Pragma("unroll") for (int n = 0; n < 2; ++n) _Pragma("unroll") for (int k = 0; k < 2; ++k) \
;         acc[ai][bj][m][n] = __builtin_amdgcn_mfma_f32_16x16x32_bf16(Bt[n][k], At[m][k], acc[ai][bj][m][n], 0, 0, 0); __builtin_amdgcn_s_setprio(0); } while (0)
; #define PG8_WAIT_L(n) asm volatile("s_waitcnt lgkmcnt(" #n ")" ::: "memory")
; #define PG8_BAR __builtin_amdgcn_s_barrier()
; #define PG8_SCHED __builtin_amdgcn_sched_barrier(0)
; template <class Epi>
; __device__ __forceinline__ void gemm_phase(const int tid, LAS unsigned char* lds, const Gemm g, const StaticOrder& S, const Epi& E) {
;     ...
;             PG8_BAR; PG8_MMA(1, 1, At, B1); PG8_BAR;
;             PG8_LDB(B0, 1, 0); PG8_SCHED; PG8_LDA(At, 1, 0); PG8_STAGE(PG8_SA(0, 1), a2 + hstep, voffA);
;             PG8_WAIT_L(8); PG8_BAR; PG8_WAIT_L(0); PG8_MMA(0, 0, At, B0); PG8_BAR; PG8_SCHED;
;             PG8_LDB(B1, 1, 1); PG8_STAGE(PG8_SB(1, 0), b3, voffB);
;             PG8_BAR; PG8_WAIT_L(0); PG8_MMA(0, 1, At, B1); PG8_BAR;
;             PG8_LDA(At, 1, 1); PG8_STAGE(PG8_SA(1, 0), a3, voffA);
.Lws_b1:
	s_barrier
	s_setprio 1
	v_mfma_f32_16x16x32_bf16 v[58:61], v[192:195], v[160:163], v[58:61]
	v_mfma_f32_16x16x32_bf16 v[50:53], v[200:203], v[160:163], v[50:53]
	v_mfma_f32_16x16x32_bf16 v[42:45], v[192:195], v[168:171], v[42:45]
	v_mfma_f32_16x16x32_bf16 v[34:37], v[200:203], v[168:171], v[34:37]
	v_mfma_f32_16x16x32_bf16 v[26:29], v[192:195], v[176:179], v[26:29]
	v_mfma_f32_16x16x32_bf16 v[18:21], v[200:203], v[176:179], v[18:21]
	v_mfma_f32_16x16x32_bf16 v[10:13], v[192:195], v[184:187], v[10:13]
	v_mfma_f32_16x16x32_bf16 v[2:5], v[200:203], v[184:187], v[2:5]
	v_mfma_f32_16x16x32_bf16 v[58:61], v[196:199], v[164:167], v[58:61]
	v_mfma_f32_16x16x32_bf16 v[50:53], v[204:207], v[164:167], v[50:53]
	v_mfma_f32_16x16x32_bf16 v[42:45], v[196:199], v[172:175], v[42:45]
	v_mfma_f32_16x16x32_bf16 v[34:37], v[204:207], v[172:175], v[34:37]
	v_mfma_f32_16x16x32_bf16 v[26:29], v[196:199], v[180:183], v[26:29]
	v_mfma_f32_16x16x32_bf16 v[18:21], v[204:207], v[180:183], v[18:21]
	v_mfma_f32_16x16x32_bf16 v[10:13], v[196:199], v[188:191], v[10:13]
	v_mfma_f32_16x16x32_bf16 v[2:5], v[204:207], v[188:191], v[2:5]
	s_setprio 0
	s_add_i32 s68, 0, 0x18000
	v_add_u32_e32 v150, s68, v155
	s_barrier
	ds_read_b128 v[130:133], v150
	ds_read_b128 v[142:145], v150 offset:1024
	ds_read_b128 v[146:149], v150 offset:2048
	ds_read_b128 v[150:153], v150 offset:3072
	s_add_u32 s66, s24, 0x80000
	s_addc_u32 s67, s25, 0
	s_mov_b32 m0, s39
	ds_read_b128 v[160:163], v158 offset:32768
	ds_read_b128 v[164:167], v158 offset:33792
	ds_read_b128 v[168:171], v158 offset:34816
	ds_read_b128 v[172:175], v158 offset:35840
	ds_read_b128 v[176:179], v158 offset:36864
	ds_read_b128 v[180:183], v158 offset:37888
	ds_read_b128 v[184:187], v158 offset:38912
	ds_read_b128 v[188:191], v158 offset:39936
	global_load_lds_dwordx4 v138, s[66:67]
	s_mov_b32 m0, s46
	s_nop 0
	global_load_lds_dwordx4 v136, s[66:67]
	s_waitcnt lgkmcnt(8)
	s_barrier
	s_setprio 1
	s_waitcnt lgkmcnt(7)
	v_mfma_f32_16x16x32_bf16 v[126:129], v[130:133], v[160:163], v[126:129]
	v_mfma_f32_16x16x32_bf16 v[118:121], v[146:149], v[160:163], v[118:121]
	s_waitcnt lgkmcnt(5)
	v_mfma_f32_16x16x32_bf16 v[110:113], v[130:133], v[168:171], v[110:113]
	v_mfma_f32_16x16x32_bf16 v[102:105], v[146:149], v[168:171], v[102:105]
	s_waitcnt lgkmcnt(3)
	v_mfma_f32_16x16x32_bf16 v[94:97], v[130:133], v[176:179], v[94:97]
	v_mfma_f32_16x16x32_bf16 v[86:89], v[146:149], v[176:179], v[86:89]
	s_waitcnt lgkmcnt(1)
	v_mfma_f32_16x16x32_bf16 v[78:81], v[130:133], v[184:187], v[78:81]
	v_mfma_f32_16x16x32_bf16 v[70:73], v[146:149], v[184:187], v[70:73]
	v_mfma_f32_16x16x32_bf16 v[126:129], v[142:145], v[164:167], v[126:129]
	v_mfma_f32_16x16x32_bf16 v[118:121], v[150:153], v[164:167], v[118:121]
	v_mfma_f32_16x16x32_bf16 v[110:113], v[142:145], v[172:175], v[110:113]
	v_mfma_f32_16x16x32_bf16 v[102:105], v[150:153], v[172:175], v[102:105]
	v_mfma_f32_16x16x32_bf16 v[94:97], v[142:145], v[180:183], v[94:97]
	v_mfma_f32_16x16x32_bf16 v[86:89], v[150:153], v[180:183], v[86:89]
	s_waitcnt lgkmcnt(0)
	v_mfma_f32_16x16x32_bf16 v[78:81], v[142:145], v[188:191], v[78:81]
	v_mfma_f32_16x16x32_bf16 v[70:73], v[150:153], v[188:191], v[70:73]
	s_setprio 0
	s_barrier
	s_add_i32 s66, 0, 0x1c000
	s_add_i32 s67, s68, s28
	v_add_u32_e32 v159, s66, v155
	s_add_i32 m0, s67, 0xffffff80
	ds_read_b128 v[192:195], v159
	ds_read_b128 v[196:199], v159 offset:1024
	ds_read_b128 v[200:203], v159 offset:2048
	ds_read_b128 v[204:207], v159 offset:3072
	global_load_lds_dwordx4 v0, s[36:37] offset:128
	s_add_i32 m0, s67, 0x1f80
	s_nop 0
	global_load_lds_dwordx4 v134, s[36:37] offset:128
	s_barrier
	s_setprio 1
	s_waitcnt lgkmcnt(3)
	v_mfma_f32_16x16x32_bf16 v[122:125], v[192:195], v[160:163], v[122:125]
	s_waitcnt lgkmcnt(1)
	v_mfma_f32_16x16x32_bf16 v[114:117], v[200:203], v[160:163], v[114:117]
	v_mfma_f32_16x16x32_bf16 v[106:109], v[192:195], v[168:171], v[106:109]
	v_mfma_f32_16x16x32_bf16 v[98:101], v[200:203], v[168:171], v[98:101]
	v_mfma_f32_16x16x32_bf16 v[90:93], v[192:195], v[176:179], v[90:93]
	v_mfma_f32_16x16x32_bf16 v[82:85], v[200:203], v[176:179], v[82:85]
	v_mfma_f32_16x16x32_bf16 v[74:77], v[192:195], v[184:187], v[74:77]
	v_mfma_f32_16x16x32_bf16 v[66:69], v[200:203], v[184:187], v[66:69]
	v_mfma_f32_16x16x32_bf16 v[122:125], v[196:199], v[164:167], v[122:125]
	s_waitcnt lgkmcnt(0)
	v_mfma_f32_16x16x32_bf16 v[114:117], v[204:207], v[164:167], v[114:117]
	v_mfma_f32_16x16x32_bf16 v[106:109], v[196:199], v[172:175], v[106:109]
	v_mfma_f32_16x16x32_bf16 v[98:101], v[204:207], v[172:175], v[98:101]
	v_mfma_f32_16x16x32_bf16 v[90:93], v[196:199], v[180:183], v[90:93]
	v_mfma_f32_16x16x32_bf16 v[82:85], v[204:207], v[180:183], v[82:85]
	v_mfma_f32_16x16x32_bf16 v[74:77], v[196:199], v[188:191], v[74:77]
	v_mfma_f32_16x16x32_bf16 v[66:69], v[204:207], v[188:191], v[66:69]
	s_setprio 0
	s_add_i32 m0, s47, 0xffffff80
	s_barrier
	ds_read_b128 v[160:163], v158 offset:49152
	ds_read_b128 v[164:167], v158 offset:50176
	ds_read_b128 v[168:171], v158 offset:51200
	ds_read_b128 v[172:175], v158 offset:52224
	ds_read_b128 v[176:179], v158 offset:53248
	ds_read_b128 v[180:183], v158 offset:54272
	ds_read_b128 v[184:187], v158 offset:55296
	ds_read_b128 v[188:191], v158 offset:56320
	global_load_lds_dwordx4 v138, s[24:25] offset:128
	s_add_i32 m0, s48, 0xffffff80
	s_nop 0
	global_load_lds_dwordx4 v136, s[24:25] offset:128
	s_barrier
; #define PG8_STAGE(bufoff, gbase, voff) do { _Pragma("unroll") for (int _i = 0; _i < 2; ++_i) \
;         __builtin_amdgcn_global_load_lds((const unsigned*)((const char*)(gbase) + (voff)[_i]), (LAS unsigned*)(lds + (bufoff) + ldsw + _i * 8192), 16, 0, 0); } while (0)
; #define PG8_LDA(dst, b, h) do { _Pragma("unroll") for (int m = 0; m < 4; ++m) _Pragma("unroll") for (int k = 0; k < 2; ++k) dst[m][k] = *(const LAS bf16x8*)(lds + PG8_SA(b, h) + aoff + m * 2048 + k * 1024); } while (0)
; #define PG8_MMA(ai, bj, At, Bt) do { __builtin_amdgcn_s_setprio(1); _Pragma("unroll") for (int m = 0; m < 4; ++m) _Pragma("unroll") for (int n = 0; n < 2; ++n) _Pragma("unroll") for (int k = 0; k < 2; ++k) \
;         acc[ai][bj][m][n] = __builtin_amdgcn_mfma_f32_16x16x32_bf16(Bt[n][k], At[m][k], acc[ai][bj][m][n], 0, 0, 0); __builtin_amdgcn_s_setprio(0); } while (0)
; #define PG8_WAIT_V(n) asm volatile("s_waitcnt vmcnt(" #n ")" ::: "memory")
; #define PG8_WAIT_L(n) asm volatile("s_waitcnt lgkmcnt(" #n ")" ::: "memory")
; #define PG8_BAR __builtin_amdgcn_s_barrier()
; #define PG8_SCHED __builtin_amdgcn_sched_barrier(0)
; template <class Epi>
; __device__ __forceinline__ void gemm_phase(const int tid, LAS unsigned char* lds, const Gemm g, const StaticOrder& S, const Epi& E) {
;     ...
;             PG8_LDA(At, 1, 1); PG8_STAGE(PG8_SA(1, 0), a3, voffA);
;             PG8_BAR; PG8_WAIT_L(0); PG8_MMA(1, 0, At, B0); PG8_BAR; PG8_SCHED;
;             PG8_STAGE(PG8_SB(1, 1), b3 + hstep, voffB);
;             PG8_WAIT_V(6); PG8_BAR; PG8_STAGE(PG8_SA(1, 1), a3 + hstep, voffA);
;             PG8_MMA(1, 1, At, B1); PG8_BAR;
;         }
	s_setprio 1
	s_waitcnt lgkmcnt(7)
	v_mfma_f32_16x16x32_bf16 v[62:65], v[130:133], v[160:163], v[62:65]
	v_mfma_f32_16x16x32_bf16 v[54:57], v[146:149], v[160:163], v[54:57]
	s_waitcnt lgkmcnt(5)
	v_mfma_f32_16x16x32_bf16 v[46:49], v[130:133], v[168:171], v[46:49]
	v_mfma_f32_16x16x32_bf16 v[38:41], v[146:149], v[168:171], v[38:41]
	s_waitcnt lgkmcnt(3)
	v_mfma_f32_16x16x32_bf16 v[30:33], v[130:133], v[176:179], v[30:33]
	v_mfma_f32_16x16x32_bf16 v[22:25], v[146:149], v[176:179], v[22:25]
	s_waitcnt lgkmcnt(1)
	v_mfma_f32_16x16x32_bf16 v[14:17], v[130:133], v[184:187], v[14:17]
	v_mfma_f32_16x16x32_bf16 v[6:9], v[146:149], v[184:187], v[6:9]
	v_mfma_f32_16x16x32_bf16 v[62:65], v[142:145], v[164:167], v[62:65]
	v_mfma_f32_16x16x32_bf16 v[54:57], v[150:153], v[164:167], v[54:57]
	v_mfma_f32_16x16x32_bf16 v[46:49], v[142:145], v[172:175], v[46:49]
	v_mfma_f32_16x16x32_bf16 v[38:41], v[150:153], v[172:175], v[38:41]
	v_mfma_f32_16x16x32_bf16 v[30:33], v[142:145], v[180:183], v[30:33]
	v_mfma_f32_16x16x32_bf16 v[22:25], v[150:153], v[180:183], v[22:25]
	s_waitcnt lgkmcnt(0)
	v_mfma_f32_16x16x32_bf16 v[14:17], v[142:145], v[188:191], v[14:17]
	v_mfma_f32_16x16x32_bf16 v[6:9], v[150:153], v[188:191], v[6:9]
	s_setprio 0
	s_barrier
	s_add_u32 s36, s36, 0x80080
	s_addc_u32 s37, s37, 0
	s_add_i32 s66, s66, s28
	s_mov_b32 m0, s66
	s_nop 0
	global_load_lds_dwordx4 v0, s[36:37]
	s_add_i32 m0, s66, 0x2000
	s_add_u32 s24, s24, 0x80080
	s_addc_u32 s25, s25, 0
	global_load_lds_dwordx4 v134, s[36:37]
	s_mov_b32 m0, s49
	s_waitcnt vmcnt(6)
	s_barrier
	global_load_lds_dwordx4 v138, s[24:25]
	s_mov_b32 m0, s50
	s_nop 0
	global_load_lds_dwordx4 v136, s[24:25]
	s_setprio 1
	v_mfma_f32_16x16x32_bf16 v[58:61], v[192:195], v[160:163], v[58:61]
	v_mfma_f32_16x16x32_bf16 v[50:53], v[200:203], v[160:163], v[50:53]
	v_mfma_f32_16x16x32_bf16 v[42:45], v[192:195], v[168:171], v[42:45]
	v_mfma_f32_16x16x32_bf16 v[34:37], v[200:203], v[168:171], v[34:37]
	v_mfma_f32_16x16x32_bf16 v[26:29], v[192:195], v[176:179], v[26:29]
	v_mfma_f32_16x16x32_bf16 v[18:21], v[200:203], v[176:179], v[18:21]
	v_mfma_f32_16x16x32_bf16 v[10:13], v[192:195], v[184:187], v[10:13]
	v_mfma_f32_16x16x32_bf16 v[2:5], v[200:203], v[184:187], v[2:5]
	v_mfma_f32_16x16x32_bf16 v[58:61], v[196:199], v[164:167], v[58:61]
	v_mfma_f32_16x16x32_bf16 v[50:53], v[204:207], v[164:167], v[50:53]
	v_mfma_f32_16x16x32_bf16 v[42:45], v[196:199], v[172:175], v[42:45]
	v_mfma_f32_16x16x32_bf16 v[34:37], v[204:207], v[172:175], v[34:37]
	v_mfma_f32_16x16x32_bf16 v[26:29], v[196:199], v[180:183], v[26:29]
	v_mfma_f32_16x16x32_bf16 v[18:21], v[204:207], v[180:183], v[18:21]
	v_mfma_f32_16x16x32_bf16 v[10:13], v[196:199], v[188:191], v[10:13]
	v_mfma_f32_16x16x32_bf16 v[2:5], v[204:207], v[188:191], v[2:5]
	s_setprio 0
	s_add_i32 s65, s65, 2
	s_add_u32 s59, s59, 0x100
	s_addc_u32 s60, s60, 0
	s_add_u32 s61, s61, 0x100
	s_addc_u32 s64, s64, 0
	s_cmp_gt_u32 s65, 29
	s_barrier
	s_cbranch_scc0 .LBB0_448
	v_lshl_add_u32 v150, s51, 8, v154
	s_cmp_lg_u32 s56, s51
	v_ashrrev_i32_e32 v151, 31, v150
	s_mov_b64 s[22:23], -1
	v_or_b32_e32 v148, 16, v150
	v_or_b32_e32 v146, 32, v150
	v_or_b32_e32 v144, 48, v150
	v_add_u32_e32 v152, 0x80, v150
	s_cbranch_scc0 .LBB0_453
; __device__ __forceinline__ void rows_rstd4(const float* ssqp, int rbase, int fq, float (&rs)[4]) {
;     f32x4 pa_[4], pb_[4];
; #pragma unroll
;     for (int m = 0; m < 4; ++m) { const float* q = ssqp + (size_t)(rbase + m * 16) * 32 + 8 * fq; pa_[m] = *(const f32x4*)q; pb_[m] = *(const f32x4*)(q + 4); }
;     asm volatile("" ::: "memory");
; #pragma unroll
;     for (int m = 0; m < 4; ++m) { const f32x4 a = pa_[m], b = pb_[m];
;         float t = ((a[0] + a[1]) + (a[2] + a[3])) + ((b[0] + b[1]) + (b[2] + b[3]));
;         t = xadd<16>(t); t = xadd<32>(t);
;         rs[m] = __builtin_amdgcn_rsqf(t * (1.0f / DM) + EPS); }
; }
;     __device__ __forceinline__ void operator()(const AccT& acc, const pg8::Unit& u, int wr, int wc, int fr, int fq, pg8::RsCache& rsc) const {
;     ...
;         if (rsc.pm != u.pm) {
;             float r0[4], r1[4]; rows_rstd4(ssq, row0, fq, r0); rows_rstd4(ssq, row0 + 128, fq, r1);
;             if (fq == 0) {
; #pragma unroll
;                 for (int m = 0; m < 4; ++m) { rsc.rl[m * 16 + fr] = r0[m]; rsc.rl[64 + m * 16 + fr] = r1[m]; } }
;             rsc.pm = u.pm; asm volatile("s_waitcnt lgkmcnt(0)" ::: "memory"); }
	v_lshlrev_b64 v[130:131], 7, v[150:151]
	v_lshl_add_u64 v[130:131], v[140:141], 0, v[130:131]
	global_load_dwordx4 v[160:163], v[130:131], off offset:16
	global_load_dwordx4 v[164:167], v[130:131], off
	v_ashrrev_i32_e32 v149, 31, v148
	v_lshlrev_b64 v[132:133], 7, v[148:149]
	v_lshl_add_u64 v[132:133], v[140:141], 0, v[132:133]
	global_load_dwordx4 v[168:171], v[132:133], off offset:16
	global_load_dwordx4 v[172:175], v[132:133], off
	v_ashrrev_i32_e32 v147, 31, v146
	v_lshlrev_b64 v[132:133], 7, v[146:147]
	v_lshl_add_u64 v[132:133], v[140:141], 0, v[132:133]
	global_load_dwordx4 v[176:179], v[132:133], off offset:16
	global_load_dwordx4 v[180:183], v[132:133], off
	v_ashrrev_i32_e32 v145, 31, v144
	v_lshlrev_b64 v[132:133], 7, v[144:145]
	v_lshl_add_u64 v[132:133], v[140:141], 0, v[132:133]
	global_load_dwordx4 v[184:187], v[132:133], off offset:16
	global_load_dwordx4 v[188:191], v[132:133], off
	s_movk_i32 s11, 0x4000
	s_mov_b64 s[22:23], 0x4800
	s_waitcnt vmcnt(0)
	v_add_f32_e32 v142, v162, v163
	v_add_f32_e32 v132, v164, v165
	v_add_f32_e32 v133, v166, v167
	v_add_f32_e32 v132, v132, v133
	v_add_f32_e32 v133, v160, v161
	v_add_f32_e32 v133, v133, v142
	v_add_f32_e32 v132, v132, v133
	ds_swizzle_b32 v133, v132 offset:swizzle(SWAP,16)
	v_add_f32_e32 v142, v170, v171
	s_waitcnt lgkmcnt(0)
	v_add_f32_e32 v151, v132, v133
	v_add_f32_e32 v132, v172, v173
	v_add_f32_e32 v133, v174, v175
	v_add_f32_e32 v132, v132, v133
	v_add_f32_e32 v133, v168, v169
	v_add_f32_e32 v133, v133, v142
	v_add_f32_e32 v132, v132, v133
	ds_swizzle_b32 v133, v132 offset:swizzle(SWAP,16)
	v_add_f32_e32 v142, v178, v179
	v_add_co_u32_e32 v174, vcc, s11, v130
	s_movk_i32 s11, 0x5000
	s_waitcnt lgkmcnt(0)
	v_add_f32_e32 v159, v132, v133
	v_add_f32_e32 v132, v180, v181
	v_add_f32_e32 v133, v182, v183
	v_add_f32_e32 v132, v132, v133
	v_add_f32_e32 v133, v176, v177
	v_add_f32_e32 v133, v133, v142
	v_add_f32_e32 v132, v132, v133
	ds_swizzle_b32 v133, v132 offset:swizzle(SWAP,16)
	v_add_f32_e32 v142, v186, v187
	v_addc_co_u32_e32 v175, vcc, 0, v131, vcc
	v_mov_b32_e32 v153, v151
	s_waitcnt lgkmcnt(0)
	v_add_f32_e32 v161, v132, v133
	v_add_f32_e32 v132, v188, v189
	v_add_f32_e32 v133, v190, v191
	v_add_f32_e32 v132, v132, v133
	v_add_f32_e32 v133, v184, v185
	v_add_f32_e32 v133, v133, v142
	v_add_f32_e32 v132, v132, v133
	ds_swizzle_b32 v133, v132 offset:swizzle(SWAP,16)
	v_add_u32_e32 v142, 0x80, v150
	v_ashrrev_i32_e32 v143, 31, v142
	v_add_co_u32_e32 v190, vcc, s11, v130
	s_waitcnt lgkmcnt(0)
	v_add_f32_e32 v163, v132, v133
	v_lshlrev_b64 v[132:133], 7, v[142:143]
	v_lshl_add_u64 v[132:133], v[140:141], 0, v[132:133]
	global_load_dwordx4 v[166:169], v[132:133], off offset:16
	global_load_dwordx4 v[170:173], v[132:133], off
	v_lshl_add_u64 v[132:133], v[130:131], 0, s[22:23]
	global_load_dwordx4 v[174:177], v[174:175], off offset:2048
	s_nop 0
	global_load_dwordx4 v[178:181], v[132:133], off offset:16
	s_mov_b64 s[22:23], 0x5000
	v_lshl_add_u64 v[132:133], v[130:131], 0, s[22:23]
	v_addc_co_u32_e32 v191, vcc, 0, v131, vcc
	s_mov_b64 s[22:23], 0x5800
	global_load_dwordx4 v[182:185], v[190:191], off
	global_load_dwordx4 v[186:189], v[132:133], off offset:16
	v_lshl_add_u64 v[130:131], v[130:131], 0, s[22:23]
	global_load_dwordx4 v[190:193], v[190:191], off offset:2048
	s_nop 0
	global_load_dwordx4 v[130:133], v[130:131], off offset:16
	v_mov_b32_e32 v160, v159
	v_mov_b32_e32 v162, v161
	v_mov_b32_e32 v164, v163
	v_permlane32_swap_b32_e32 v151, v153
	v_permlane32_swap_b32_e32 v159, v160
	v_permlane32_swap_b32_e32 v161, v162
	v_permlane32_swap_b32_e32 v163, v164
	s_waitcnt vmcnt(7)
	v_add_f32_e32 v166, v166, v167
	v_add_f32_e32 v167, v168, v169
	v_add_f32_e32 v166, v166, v167
	s_waitcnt vmcnt(5)
	v_add_f32_e32 v167, v174, v175
	v_add_f32_e32 v168, v176, v177
	v_add_f32_e32 v165, v170, v171
	v_add_f32_e32 v170, v172, v173
	v_add_f32_e32 v167, v167, v168
	s_waitcnt vmcnt(4)
	v_add_f32_e32 v168, v178, v179
	v_add_f32_e32 v169, v180, v181
	v_add_f32_e32 v165, v165, v170
	v_add_f32_e32 v168, v168, v169
	s_waitcnt vmcnt(3)
	v_add_f32_e32 v169, v182, v183
	v_add_f32_e32 v170, v184, v185
	v_add_f32_e32 v169, v169, v170
	s_waitcnt vmcnt(2)
	v_add_f32_e32 v170, v186, v187
	v_add_f32_e32 v171, v188, v189
	v_add_f32_e32 v170, v170, v171
	s_waitcnt vmcnt(1)
	v_add_f32_e32 v171, v190, v191
	v_add_f32_e32 v172, v192, v193
	s_waitcnt vmcnt(0)
	v_add_f32_e32 v130, v130, v131
	v_add_f32_e32 v131, v132, v133
	v_add_f32_e32 v171, v171, v172
	v_add_f32_e32 v130, v130, v131
	v_add_f32_e32 v165, v165, v166
	v_add_f32_e32 v167, v167, v168
	v_add_f32_e32 v169, v169, v170
	v_add_f32_e32 v130, v171, v130
	ds_swizzle_b32 v166, v165 offset:swizzle(SWAP,16)
	ds_swizzle_b32 v168, v167 offset:swizzle(SWAP,16)
	ds_swizzle_b32 v170, v169 offset:swizzle(SWAP,16)
	ds_swizzle_b32 v131, v130 offset:swizzle(SWAP,16)
	s_waitcnt lgkmcnt(3)
	v_add_f32_e32 v165, v165, v166
	s_waitcnt lgkmcnt(2)
	v_add_f32_e32 v167, v167, v168
	s_waitcnt lgkmcnt(1)
	v_add_f32_e32 v169, v169, v170
	s_waitcnt lgkmcnt(0)
	v_add_f32_e32 v130, v130, v131
	v_mov_b32_e32 v166, v165
	v_mov_b32_e32 v168, v167
	v_mov_b32_e32 v170, v169
	v_mov_b32_e32 v131, v130
	v_permlane32_swap_b32_e32 v165, v166
	v_permlane32_swap_b32_e32 v167, v168
	v_permlane32_swap_b32_e32 v169, v170
	v_permlane32_swap_b32_e32 v130, v131
	s_and_saveexec_b64 s[22:23], s[4:5]
	s_cbranch_execz .LBB0_452
	v_add_f32_e32 v159, v159, v160
	v_add_f32_e32 v151, v151, v153
	v_add_f32_e32 v132, v167, v168
	v_add_f32_e32 v133, v165, v166
	v_fmamk_f32 v159, v159, 0x3a000000, v242
	v_fmamk_f32 v151, v151, 0x3a000000, v242
	v_fmamk_f32 v132, v132, 0x3a000000, v242
	v_fmamk_f32 v133, v133, 0x3a000000, v242
	v_add_f32_e32 v163, v163, v164
	v_add_f32_e32 v161, v161, v162
	v_rsq_f32_e32 v159, v159
	v_rsq_f32_e32 v151, v151
	v_add_f32_e32 v130, v130, v131
	v_add_f32_e32 v131, v169, v170
	v_rsq_f32_e32 v132, v132
	v_rsq_f32_e32 v133, v133
	v_fmamk_f32 v163, v163, 0x3a000000, v242
	v_fmamk_f32 v153, v161, 0x3a000000, v242
	v_fmamk_f32 v130, v130, 0x3a000000, v242
	v_fmamk_f32 v131, v131, 0x3a000000, v242
	v_rsq_f32_e32 v163, v163
	v_rsq_f32_e32 v153, v153
	v_rsq_f32_e32 v130, v130
	v_rsq_f32_e32 v131, v131
	ds_write2_b32 v156, v151, v159 offset1:16
	ds_write2_b32 v156, v133, v132 offset0:64 offset1:80
	ds_write2_b32 v156, v153, v163 offset0:32 offset1:48
	ds_write2_b32 v156, v131, v130 offset0:96 offset1:112
